# v9 + attention: saddr-form K/V staging loads (13 v_lshl_add_u64 removed), persistent softmax-reference broadcast registers in the GQA mixer
# speedup vs baseline: 1.0072x; 1.0033x over previous
.LBB0_64:
	s_and_b64 vcc, exec, s[0:1]
	s_cbranch_vccz .LBB0_74
	s_add_i32 s0, s70, s59
	s_ashr_i32 s1, s0, 31
	v_mov_b32_e32 v8, v222
	s_add_u32 s0, s0, s24
	v_readlane_b32 s26, v251, 57
	s_addc_u32 s1, s1, s25
	v_and_b32_e32 v0, 31, v8
	v_readlane_b32 s27, v251, 58
	s_waitcnt vmcnt(0)
	v_lshl_add_u64 v[146:147], s[0:1], 0, v[0:1]
	v_ashrrev_i32_e32 v158, 5, v8
	v_mov_b64_e32 v[2:3], s[26:27]
	v_mad_u64_u32 v[2:3], s[0:1], v146, s84, v[2:3]
	s_lshl_b32 s0, s68, 7
	v_mad_i32_i24 v3, v147, s84, v3
	s_ashr_i32 s1, s0, 31
	v_lshlrev_b32_e32 v4, 3, v158
	v_lshl_add_u64 v[2:3], s[0:1], 1, v[2:3]
	v_ashrrev_i32_e32 v5, 31, v4
	v_lshl_add_u64 v[2:3], v[4:5], 1, v[2:3]
	s_mov_b64 s[28:29], 0x1000
	s_movk_i32 s40, 0x1000
	v_lshl_add_u64 v[4:5], v[2:3], 0, s[28:29]
	s_mul_i32 s74, s24, 0x2800
	v_add_co_u32_e32 v2, vcc, s40, v2
	s_mul_hi_i32 s73, s24, 0x2800
	s_add_u32 s30, s26, s74
	v_mov_b32_e32 v38, v223
	v_addc_co_u32_e32 v3, vcc, 0, v3, vcc
	s_addc_u32 s31, s27, s73
	s_lshl_b32 s26, s68, 6
	global_load_dwordx4 v[98:101], v[2:3], off
	global_load_dwordx4 v[102:105], v[4:5], off offset:32
	global_load_dwordx4 v[106:109], v[4:5], off offset:64
	global_load_dwordx4 v[110:113], v[4:5], off offset:96
	global_load_dwordx4 v[114:117], v[4:5], off offset:128
	global_load_dwordx4 v[118:121], v[4:5], off offset:160
	global_load_dwordx4 v[122:125], v[4:5], off offset:192
	global_load_dwordx4 v[126:129], v[4:5], off offset:224
	v_ashrrev_i32_e32 v2, 31, v38
	s_and_b32 s28, s26, 0xffffff80
	v_lshrrev_b32_e32 v2, 28, v2
	s_ashr_i32 s29, s28, 31
	v_add_u32_e32 v2, v38, v2
	s_lshl_b64 s[26:27], s[28:29], 1
	v_ashrrev_i32_e32 v39, 4, v2
	v_and_b32_e32 v2, -16, v2
	v_add_u32_e32 v13, 0x200, v38
	s_add_u32 s29, s30, s26
	v_sub_u32_e32 v12, v38, v2
	v_ashrrev_i32_e32 v2, 31, v13
	s_addc_u32 s30, s31, s27
	v_lshlrev_b32_e32 v6, 1, v8
	v_lshrrev_b32_e32 v2, 28, v2
	s_add_u32 s42, s29, 0x1400
	v_and_b32_e32 v9, 8, v6
	v_lshrrev_b32_e32 v6, 1, v8
	v_add_u32_e32 v2, v13, v2
	s_addc_u32 s43, s30, 0
	v_and_b32_e32 v10, 4, v6
	v_ashrrev_i32_e32 v40, 4, v2
	v_and_b32_e32 v2, -16, v2
	v_lshlrev_b32_e32 v6, 3, v12
	v_sub_u32_e32 v14, v13, v2
	v_mov_b64_e32 v[2:3], s[42:43]
	v_ashrrev_i32_e32 v7, 31, v6
	v_mad_i64_i32 v[4:5], s[42:43], v39, s84, v[2:3]
	v_lshlrev_b64 v[34:35], 1, v[6:7]
	v_lshl_add_u64 v[4:5], v[4:5], 0, v[34:35]
	s_addk_i32 s28, 0x200
	global_load_dwordx4 v[130:133], v[4:5], off
	v_lshlrev_b32_e32 v4, 3, v14
	s_mul_hi_i32 s31, s28, 0xc000
	s_mul_i32 s30, s28, 0xc000
	v_readlane_b32 s28, v251, 59
	v_ashrrev_i32_e32 v5, 31, v4
	v_readlane_b32 s29, v251, 60
	s_add_u32 s34, s28, s30
	v_mad_i64_i32 v[2:3], s[42:43], v40, s84, v[2:3]
	v_lshlrev_b64 v[36:37], 1, v[4:5]
	s_addc_u32 s35, s29, s31
	s_lshl_b64 s[28:29], s[24:25], 1
	v_lshl_add_u64 v[2:3], v[2:3], 0, v[36:37]
	s_add_u32 s34, s34, s28
	global_load_dwordx4 v[134:137], v[2:3], off
	v_lshlrev_b32_e32 v2, 4, v38
	s_addc_u32 s35, s35, s29
	v_and_b32_e32 v148, 0x70, v2
	v_mov_b32_e32 v149, v1
	v_lshl_add_u64 v[2:3], s[34:35], 0, v[148:149]
	v_ashrrev_i32_e32 v41, 3, v38
	v_mad_i64_i32 v[4:5], s[34:35], v41, s85, v[2:3]
	v_ashrrev_i32_e32 v46, 3, v13
	global_load_dwordx4 v[138:141], v[4:5], off
	v_mad_i64_i32 v[2:3], s[34:35], v46, s85, v[2:3]
	global_load_dwordx4 v[142:145], v[2:3], off
	s_movk_i32 s34, 0x110
	v_mul_lo_u32 v149, v39, s34
	v_lshlrev_b32_e32 v159, 4, v12
	v_add3_u32 v2, 0, v149, v159
	v_mul_lo_u32 v160, v40, s34
	v_lshlrev_b32_e32 v161, 4, v14
	s_movk_i32 s35, 0x90
	v_mul_lo_u32 v162, v41, s35
	v_mul_lo_u32 v163, v46, s35
	v_and_b32_e32 v11, 19, v8
	v_mul_u32_u24_e32 v166, 0x90, v0
	s_mov_b32 s35, 0xc2700000
	s_mov_b32 s40, 0
	s_mov_b32 s41, s40
	s_mov_b32 s42, s40
	s_mov_b32 s43, s40
	s_mov_b32 s44, s40
	s_mov_b32 s45, s40
	s_mov_b32 s46, s40
	s_mov_b32 s47, s40
	s_mov_b32 s48, s40
	s_mov_b32 s49, s40
	s_mov_b32 s50, s40
	s_mov_b32 s51, s40
	s_mov_b32 s52, s40
	s_mov_b32 s53, s40
	s_mov_b32 s54, s40
	s_mov_b32 s55, s40
	s_add_u32 s26, s26, s74
	s_addc_u32 s27, s27, s73
	s_mov_b64 s[74:75], 0x100
	v_mov_b32_e32 v169, 0
	s_waitcnt vmcnt(3)
	ds_write_b128 v2, v[130:133]
	v_add3_u32 v2, 0, v160, v161
	s_waitcnt vmcnt(2)
	ds_write_b128 v2, v[134:137]
	v_add_u32_e32 v2, 0, v148
	v_add_u32_e32 v3, v2, v162
	v_add_u32_e32 v2, v2, v163
	s_waitcnt vmcnt(1)
	ds_write_b128 v3, v[138:141] offset:17408
	v_ashrrev_i32_e32 v3, 1, v8
	v_and_b32_e32 v164, -16, v3
	s_waitcnt vmcnt(0)
	ds_write_b128 v2, v[142:145] offset:17408
	v_or3_b32 v2, v11, v9, v10
	v_mad_u32_u24 v165, v2, s34, v164
	v_add_u32_e32 v0, 0, v165
	s_waitcnt lgkmcnt(0)
	s_barrier
	ds_read_b128 v[18:21], v0
	ds_read_b128 v[42:45], v0 offset:32
	s_waitcnt lgkmcnt(1)
	v_mfma_f32_32x32x16_bf16 v[18:33], v[18:21], v[98:101], 0
	v_mov_b64_e32 v[2:3], s[40:41]
	v_mov_b64_e32 v[4:5], s[42:43]
	v_mov_b64_e32 v[6:7], s[44:45]
	v_mov_b64_e32 v[8:9], s[46:47]
	v_mov_b64_e32 v[10:11], s[48:49]
	v_mov_b64_e32 v[12:13], s[50:51]
	v_mov_b64_e32 v[14:15], s[52:53]
	s_waitcnt lgkmcnt(0)
	v_mfma_f32_32x32x16_bf16 v[18:33], v[42:45], v[102:105], v[18:33]
	ds_read_b128 v[42:45], v0 offset:64
	v_mov_b64_e32 v[16:17], s[54:55]
	s_mov_b64 s[42:43], 0x1e500080
	v_mov_b64_e32 v[64:65], v[16:17]
	s_mov_b64 s[44:45], 0xa0000
	s_mov_b32 s34, 64
	v_mov_b64_e32 v[62:63], v[14:15]
	s_waitcnt lgkmcnt(0)
	v_mfma_f32_32x32x16_bf16 v[18:33], v[42:45], v[106:109], v[18:33]
	ds_read_b128 v[42:45], v0 offset:96
	v_mov_b64_e32 v[60:61], v[12:13]
	v_mov_b64_e32 v[58:59], v[10:11]
	v_mov_b64_e32 v[56:57], v[8:9]
	v_mov_b64_e32 v[54:55], v[6:7]
	v_mov_b64_e32 v[52:53], v[4:5]
	v_mov_b64_e32 v[50:51], v[2:3]
	s_waitcnt lgkmcnt(0)
	v_mfma_f32_32x32x16_bf16 v[18:33], v[42:45], v[110:113], v[18:33]
	ds_read_b128 v[42:45], v0 offset:128
	s_waitcnt lgkmcnt(0)
	v_mfma_f32_32x32x16_bf16 v[18:33], v[42:45], v[114:117], v[18:33]
	ds_read_b128 v[42:45], v0 offset:160
	s_waitcnt lgkmcnt(0)
	v_mfma_f32_32x32x16_bf16 v[18:33], v[42:45], v[118:121], v[18:33]
	ds_read_b128 v[42:45], v0 offset:192
	s_waitcnt lgkmcnt(0)
	v_mfma_f32_32x32x16_bf16 v[18:33], v[42:45], v[122:125], v[18:33]
	ds_read_b128 v[42:45], v0 offset:224
	s_waitcnt lgkmcnt(0)
	v_mfma_f32_32x32x16_bf16 v[18:33], v[42:45], v[126:129], v[18:33]
	s_nop 11
	v_max_f32_e32 v0, v18, v19
	v_max3_f32 v0, v0, v20, v21
	v_max3_f32 v0, v0, v22, v23
	v_max3_f32 v0, v0, v24, v25
	v_and_b32_e32 v19, 64, v210
	v_max3_f32 v0, v0, v26, v27
	v_xor_b32_e32 v18, 32, v210
	v_add_u32_e32 v19, 64, v19
	v_max3_f32 v0, v0, v28, v29
	v_cmp_lt_i32_e32 vcc, v18, v19
	v_max3_f32 v0, v0, v30, v31
	v_max3_f32 v0, v0, v32, v33
	v_cndmask_b32_e32 v18, v210, v18, vcc
	v_lshlrev_b32_e32 v167, 2, v18
	ds_bpermute_b32 v18, v167, v0
	s_waitcnt lgkmcnt(0)
	v_max3_f32 v168, v0, v18, s35
	v_mov_b64_e32 v[18:19], s[30:31]
	v_and_b32_e32 v0, 7, v38
	v_mad_i64_i32 v[20:21], s[30:31], v46, s85, v[18:19]
	v_lshlrev_b32_e32 v0, 4, v0
	v_mad_i64_i32 v[18:19], s[30:31], v41, s85, v[18:19]
	v_lshl_add_u64 v[18:19], v[18:19], 0, v[0:1]
	v_lshl_add_u64 v[20:21], v[20:21], 0, v[0:1]
	v_lshl_add_u64 v[18:19], v[18:19], 0, s[28:29]
	v_lshl_add_u64 v[20:21], v[20:21], 0, s[28:29]
	v_lshl_add_u64 v[152:153], v[18:19], 0, s[42:43]
	v_mov_b64_e32 v[18:19], s[26:27]
	v_lshl_add_u64 v[150:151], v[20:21], 0, s[42:43]
	v_mad_i64_i32 v[20:21], s[26:27], v39, s84, v[18:19]
	v_mad_i64_i32 v[18:19], s[26:27], v40, s84, v[18:19]
	v_lshl_add_u64 v[20:21], v[20:21], 0, v[34:35]
	s_mov_b64 s[28:29], 0xf5a1400
	v_lshl_add_u64 v[18:19], v[18:19], 0, v[36:37]
	v_lshl_add_u64 v[154:155], v[20:21], 0, s[28:29]
	v_lshl_add_u64 v[156:157], v[18:19], 0, s[28:29]
	v_mov_b64_e32 v[32:33], v[16:17]
	v_mov_b64_e32 v[48:49], v[16:17]
	v_mov_b64_e32 v[30:31], v[14:15]
	v_mov_b64_e32 v[28:29], v[12:13]
	v_mov_b64_e32 v[26:27], v[10:11]
	v_mov_b64_e32 v[24:25], v[8:9]
	v_mov_b64_e32 v[22:23], v[6:7]
	v_mov_b64_e32 v[20:21], v[4:5]
	v_mov_b64_e32 v[18:19], v[2:3]
	v_mov_b64_e32 v[46:47], v[14:15]
	v_mov_b64_e32 v[44:45], v[12:13]
	v_mov_b64_e32 v[42:43], v[10:11]
	v_mov_b64_e32 v[40:41], v[8:9]
	v_mov_b64_e32 v[38:39], v[6:7]
	v_mov_b64_e32 v[36:37], v[4:5]
	v_mov_b64_e32 v[34:35], v[2:3]
	v_xor_b32_e32 v226, 0x80000000, v168
	v_mov_b32_e32 v227, v226
	v_mov_b32_e32 v228, v226
	v_mov_b32_e32 v229, v226
	v_mov_b32_e32 v230, v226
	v_mov_b32_e32 v231, v226
	v_mov_b32_e32 v232, v226
	v_mov_b32_e32 v233, v226
	v_mov_b32_e32 v234, v226
	v_mov_b32_e32 v235, v226
	v_mov_b32_e32 v236, v226
	v_mov_b32_e32 v237, v226
	v_mov_b32_e32 v238, v226
	v_mov_b32_e32 v239, v226
	v_mov_b32_e32 v240, v226
	v_mov_b32_e32 v241, v226
	s_branch .LBB0_67

.LBB0_67:
	s_cmp_lt_u32 s34, s67
	s_cselect_b64 s[28:29], -1, 0
	s_cmp_ge_u32 s34, s67
	s_cselect_b64 s[26:27], -1, 0
	s_and_b64 vcc, exec, s[26:27]
	s_cbranch_vccnz .LBB0_69
	global_load_dwordx4 v[130:133], v154, s[88:89]
	global_load_dwordx4 v[134:137], v156, s[88:89]
	global_load_dwordx4 v[138:141], v152, s[88:89]
	global_load_dwordx4 v[142:145], v150, s[88:89]
.LBB0_69:
	s_mul_i32 s30, s40, 0xac00
	s_add_i32 s30, s30, 0
	v_add_u32_e32 v188, s30, v165
	ds_read_b128 v[170:173], v188
	ds_read_b128 v[174:177], v188 offset:32
	ds_read_b128 v[178:181], v188 offset:64
	s_waitcnt lgkmcnt(2)
	v_mfma_f32_32x32x16_bf16 v[82:97], v[170:173], v[98:101], v[226:241]
	ds_read_b128 v[170:173], v188 offset:96
	s_waitcnt lgkmcnt(2)
	v_mfma_f32_32x32x16_bf16 v[82:97], v[174:177], v[102:105], v[82:97]
	ds_read_b128 v[174:177], v188 offset:128
	s_waitcnt lgkmcnt(2)
	v_mfma_f32_32x32x16_bf16 v[82:97], v[178:181], v[106:109], v[82:97]
	ds_read_b128 v[178:181], v188 offset:160
	s_waitcnt lgkmcnt(2)
	v_mfma_f32_32x32x16_bf16 v[82:97], v[170:173], v[110:113], v[82:97]
	ds_read_b128 v[170:173], v188 offset:192
	s_waitcnt lgkmcnt(2)
	v_mfma_f32_32x32x16_bf16 v[82:97], v[174:177], v[114:117], v[82:97]
	ds_read_b128 v[174:177], v188 offset:224
	s_waitcnt lgkmcnt(2)
	v_mfma_f32_32x32x16_bf16 v[82:97], v[178:181], v[118:121], v[82:97]
	ds_read_b128 v[178:181], v188 offset:8704
	s_waitcnt lgkmcnt(2)
	v_mfma_f32_32x32x16_bf16 v[82:97], v[170:173], v[122:125], v[82:97]
	ds_read_b128 v[170:173], v188 offset:8736
	s_waitcnt lgkmcnt(2)
	v_mfma_f32_32x32x16_bf16 v[82:97], v[174:177], v[126:129], v[82:97]
	ds_read_b128 v[174:177], v188 offset:8768
	v_add3_u32 v189, s30, v166, v164
	ds_read_b128 v[182:185], v188 offset:8800
	s_waitcnt lgkmcnt(3)
	v_mfma_f32_32x32x16_bf16 v[66:81], v[178:181], v[98:101], v[226:241]
	s_nop 6
	v_exp_f32_e32 v0, v82
	v_exp_f32_e32 v178, v83
	v_max_f32_e32 v83, v82, v83
	v_add_f32_e32 v187, v0, v178
	v_cvt_pk_bf16_f32 v82, v0, v178
	ds_read_b128 v[178:181], v188 offset:8832
	s_waitcnt lgkmcnt(3)
	v_mfma_f32_32x32x16_bf16 v[66:81], v[170:173], v[102:105], v[66:81]
	v_exp_f32_e32 v186, v84
	v_exp_f32_e32 v0, v85
	v_max_f32_e32 v84, v84, v85
	v_max3_f32 v190, v83, s86, v84
	v_pk_add_f32 v[84:85], v[186:187], v[0:1]
	v_cvt_pk_bf16_f32 v83, v186, v0
	v_pk_add_f32 v[186:187], v[84:85], v[84:85] op_sel_hi:[0,1]
	ds_read_b128 v[170:173], v188 offset:8864
	s_waitcnt lgkmcnt(3)
	v_mfma_f32_32x32x16_bf16 v[66:81], v[174:177], v[106:109], v[66:81]
	v_exp_f32_e32 v84, v86
	v_exp_f32_e32 v85, v87
	v_max_f32_e32 v0, v86, v87
	v_add_f32_e32 v87, v84, v85
	v_cvt_pk_bf16_f32 v84, v84, v85
	ds_read_b128 v[174:177], v188 offset:8896
	s_waitcnt lgkmcnt(3)
	v_mfma_f32_32x32x16_bf16 v[66:81], v[182:185], v[110:113], v[66:81]
	v_exp_f32_e32 v86, v88
	v_exp_f32_e32 v186, v89
	v_max_f32_e32 v85, v88, v89
	v_pk_add_f32 v[88:89], v[86:87], v[186:187]
	v_max3_f32 v0, v190, v0, v85
	v_cvt_pk_bf16_f32 v85, v86, v186
	v_pk_add_f32 v[186:187], v[88:89], v[88:89] op_sel_hi:[0,1]
	ds_read_b128 v[86:89], v188 offset:8928
	s_waitcnt lgkmcnt(3)
	v_mfma_f32_32x32x16_bf16 v[66:81], v[178:181], v[114:117], v[66:81]
	v_exp_f32_e32 v182, v90
	v_exp_f32_e32 v184, v91
	v_max_f32_e32 v91, v90, v91
	v_add_f32_e32 v183, v182, v184
	v_cvt_pk_bf16_f32 v90, v182, v184
	ds_read_b128 v[178:181], v189 offset:17408
	s_waitcnt lgkmcnt(3)
	v_mfma_f32_32x32x16_bf16 v[66:81], v[170:173], v[118:121], v[66:81]
	v_exp_f32_e32 v182, v92
	v_exp_f32_e32 v186, v93
	v_max_f32_e32 v92, v92, v93
	v_max3_f32 v0, v0, v91, v92
	v_pk_add_f32 v[92:93], v[182:183], v[186:187]
	v_cvt_pk_bf16_f32 v91, v182, v186
	v_pk_add_f32 v[182:183], v[92:93], v[92:93] op_sel_hi:[0,1]
	ds_read_b128 v[170:173], v189 offset:22016
	s_waitcnt lgkmcnt(3)
	v_mfma_f32_32x32x16_bf16 v[66:81], v[174:177], v[122:125], v[66:81]
	v_exp_f32_e32 v93, v94
	v_exp_f32_e32 v182, v95
	v_max_f32_e32 v184, v94, v95
	v_add_f32_e32 v95, v93, v182
	v_cvt_pk_bf16_f32 v92, v93, v182
	ds_read_b128 v[174:177], v189 offset:26624
	s_waitcnt lgkmcnt(3)
	v_mfma_f32_32x32x16_bf16 v[66:81], v[86:89], v[126:129], v[66:81]
	v_exp_f32_e32 v94, v96
	v_exp_f32_e32 v182, v97
	v_max_f32_e32 v86, v96, v97
	v_max3_f32 v0, v0, v184, v86
	v_pk_add_f32 v[86:87], v[94:95], v[182:183]
	v_cvt_pk_bf16_f32 v93, v94, v182
	v_pk_add_f32 v[182:183], v[86:87], v[86:87] op_sel_hi:[0,1]
	ds_read_b128 v[86:89], v189 offset:31232
	ds_read_b128 v[94:97], v189 offset:17440
	s_waitcnt lgkmcnt(4)
	v_mfma_f32_32x32x16_bf16 v[50:65], v[178:181], v[82:85], v[50:65]
	s_nop 0
	v_exp_f32_e32 v178, v66
	v_exp_f32_e32 v179, v67
	v_max_f32_e32 v67, v66, v67
	v_add_f32_e32 v185, v178, v179
	v_cvt_pk_bf16_f32 v66, v178, v179
	ds_read_b128 v[178:181], v189 offset:22048
	s_waitcnt lgkmcnt(4)
	v_mfma_f32_32x32x16_bf16 v[34:49], v[170:173], v[82:85], v[34:49]
	v_exp_f32_e32 v182, v68
	v_exp_f32_e32 v184, v69
	v_max_f32_e32 v68, v68, v69
	v_max3_f32 v0, v0, v67, v68
	v_pk_add_f32 v[68:69], v[182:183], v[184:185]
	v_cvt_pk_bf16_f32 v67, v182, v184
	v_pk_add_f32 v[182:183], v[68:69], v[68:69] op_sel_hi:[0,1]
	ds_read_b128 v[170:173], v189 offset:26656
	s_waitcnt lgkmcnt(4)
	v_mfma_f32_32x32x16_bf16 v[18:33], v[174:177], v[82:85], v[18:33]
	v_exp_f32_e32 v68, v70
	v_exp_f32_e32 v69, v71
	v_max_f32_e32 v184, v70, v71
	v_add_f32_e32 v71, v68, v69
	v_cvt_pk_bf16_f32 v68, v68, v69
	ds_read_b128 v[174:177], v189 offset:31264
	s_waitcnt lgkmcnt(4)
	v_mfma_f32_32x32x16_bf16 v[2:17], v[86:89], v[82:85], v[2:17]
	v_exp_f32_e32 v70, v72
	v_exp_f32_e32 v182, v73
	v_max_f32_e32 v69, v72, v73
	v_pk_add_f32 v[72:73], v[70:71], v[182:183]
	v_max3_f32 v0, v0, v184, v69
	v_pk_add_f32 v[72:73], v[72:73], v[72:73] op_sel_hi:[0,1]
	v_cvt_pk_bf16_f32 v69, v70, v182
	s_waitcnt lgkmcnt(3)
	v_mfma_f32_32x32x16_bf16 v[50:65], v[94:97], v[90:93], v[50:65]
	v_exp_f32_e32 v70, v74
	v_exp_f32_e32 v71, v75
	v_max_f32_e32 v86, v74, v75
	v_add_f32_e32 v75, v70, v71
	v_cvt_pk_bf16_f32 v70, v70, v71
	v_exp_f32_e32 v74, v76
	v_exp_f32_e32 v72, v77
	v_max_f32_e32 v71, v76, v77
	v_pk_add_f32 v[76:77], v[74:75], v[72:73]
	v_max3_f32 v0, v0, v86, v71
	v_pk_add_f32 v[94:95], v[76:77], v[76:77] op_sel_hi:[0,1]
	v_cvt_pk_bf16_f32 v71, v74, v72
	ds_read_b128 v[74:77], v189 offset:22080
	s_waitcnt lgkmcnt(3)
	v_mfma_f32_32x32x16_bf16 v[34:49], v[178:181], v[90:93], v[34:49]
	ds_read_b128 v[82:85], v189 offset:17472
	s_waitcnt lgkmcnt(1)
	v_mfma_f32_32x32x16_bf16 v[34:49], v[74:77], v[66:69], v[34:49]
	ds_read_b128 v[74:77], v189 offset:26720
	v_mfma_f32_32x32x16_bf16 v[18:33], v[170:173], v[90:93], v[18:33]
	v_exp_f32_e32 v72, v78
	v_exp_f32_e32 v73, v79
	v_max_f32_e32 v170, v78, v79
	v_add_f32_e32 v79, v72, v73
	v_cvt_pk_bf16_f32 v72, v72, v73
	v_exp_f32_e32 v78, v80
	v_exp_f32_e32 v94, v81
	ds_read_b128 v[86:89], v189 offset:26688
	v_max_f32_e32 v171, v80, v81
	v_pk_add_f32 v[96:97], v[78:79], v[94:95]
	v_cvt_pk_bf16_f32 v73, v78, v94
	ds_read_b128 v[78:81], v189 offset:17504
	s_waitcnt lgkmcnt(3)
	v_mfma_f32_32x32x16_bf16 v[50:65], v[82:85], v[66:69], v[50:65]
	ds_read_b128 v[82:85], v189 offset:31296
	v_mfma_f32_32x32x16_bf16 v[2:17], v[174:177], v[90:93], v[2:17]
	ds_read_b128 v[90:93], v189 offset:22112
	s_waitcnt lgkmcnt(3)
	v_mfma_f32_32x32x16_bf16 v[18:33], v[86:89], v[66:69], v[18:33]
	ds_read_b128 v[86:89], v189 offset:31328
	v_max3_f32 v0, v0, v170, v171
	ds_bpermute_b32 v196, v167, v0
	v_add_f32_e32 v197, v96, v97
	v_add_f32_e32 v169, v169, v197
	s_xor_b32 s30, s40, 1
	s_mul_i32 s30, s30, 0xac00
	v_add_u32_e32 v192, s30, v148
	v_add3_u32 v193, s30, v149, v159
	v_add_u32_e32 v194, v192, v163
	v_add_u32_e32 v192, v192, v162
	v_add3_u32 v195, s30, v160, v161
	s_waitcnt vmcnt(3)
	ds_write_b128 v193, v[130:133]
	s_waitcnt vmcnt(2)
	ds_write_b128 v195, v[134:137]
	s_waitcnt vmcnt(1)
	ds_write_b128 v192, v[138:141] offset:17408
	s_waitcnt vmcnt(0)
	ds_write_b128 v194, v[142:145] offset:17408
	s_waitcnt lgkmcnt(7)
	v_mfma_f32_32x32x16_bf16 v[2:17], v[82:85], v[66:69], v[2:17]
	v_mfma_f32_32x32x16_bf16 v[50:65], v[78:81], v[70:73], v[50:65]
	s_waitcnt lgkmcnt(6)
	v_mfma_f32_32x32x16_bf16 v[34:49], v[90:93], v[70:73], v[34:49]
	v_mfma_f32_32x32x16_bf16 v[18:33], v[74:77], v[70:73], v[18:33]
	s_waitcnt lgkmcnt(5)
	v_mfma_f32_32x32x16_bf16 v[2:17], v[86:89], v[70:73], v[2:17]
	s_waitcnt lgkmcnt(0)
	v_max_f32_e32 v196, v196, v196
	v_max_f32_e32 v0, v0, v196
	v_cmp_lt_f32_e32 vcc, s87, v0
	s_cbranch_vccz .LBB0_71
	v_max_f32_e32 v0, v0, v0
	v_max_f32_e32 v66, 0, v0
	v_exp_f32_e64 v0, -v66
	v_add_f32_e32 v168, v168, v66
	v_xor_b32_e32 v226, 0x80000000, v168
	v_mov_b32_e32 v227, v226
	v_mov_b32_e32 v228, v226
	v_mov_b32_e32 v229, v226
	v_mov_b32_e32 v230, v226
	v_mov_b32_e32 v231, v226
	v_mov_b32_e32 v232, v226
	v_mov_b32_e32 v233, v226
	v_mov_b32_e32 v234, v226
	v_mov_b32_e32 v235, v226
	v_mov_b32_e32 v236, v226
	v_mov_b32_e32 v237, v226
	v_mov_b32_e32 v238, v226
	v_mov_b32_e32 v239, v226
	v_mov_b32_e32 v240, v226
	v_mov_b32_e32 v241, v226
	v_mul_f32_e32 v169, v169, v0
	v_pk_mul_f32 v[64:65], v[64:65], v[0:1] op_sel_hi:[1,0]
	v_pk_mul_f32 v[62:63], v[62:63], v[0:1] op_sel_hi:[1,0]
	v_pk_mul_f32 v[60:61], v[60:61], v[0:1] op_sel_hi:[1,0]
	v_pk_mul_f32 v[58:59], v[58:59], v[0:1] op_sel_hi:[1,0]
	v_pk_mul_f32 v[56:57], v[56:57], v[0:1] op_sel_hi:[1,0]
	v_pk_mul_f32 v[54:55], v[54:55], v[0:1] op_sel_hi:[1,0]
	v_pk_mul_f32 v[52:53], v[52:53], v[0:1] op_sel_hi:[1,0]
	v_pk_mul_f32 v[50:51], v[50:51], v[0:1] op_sel_hi:[1,0]
	v_pk_mul_f32 v[48:49], v[48:49], v[0:1] op_sel_hi:[1,0]
	v_pk_mul_f32 v[46:47], v[46:47], v[0:1] op_sel_hi:[1,0]
	v_pk_mul_f32 v[44:45], v[44:45], v[0:1] op_sel_hi:[1,0]
	v_pk_mul_f32 v[42:43], v[42:43], v[0:1] op_sel_hi:[1,0]
	v_pk_mul_f32 v[40:41], v[40:41], v[0:1] op_sel_hi:[1,0]
	v_pk_mul_f32 v[38:39], v[38:39], v[0:1] op_sel_hi:[1,0]
	v_pk_mul_f32 v[36:37], v[36:37], v[0:1] op_sel_hi:[1,0]
	v_pk_mul_f32 v[34:35], v[34:35], v[0:1] op_sel_hi:[1,0]
	v_pk_mul_f32 v[32:33], v[32:33], v[0:1] op_sel_hi:[1,0]
	v_pk_mul_f32 v[30:31], v[30:31], v[0:1] op_sel_hi:[1,0]
	v_pk_mul_f32 v[28:29], v[28:29], v[0:1] op_sel_hi:[1,0]
	v_pk_mul_f32 v[26:27], v[26:27], v[0:1] op_sel_hi:[1,0]
	v_pk_mul_f32 v[24:25], v[24:25], v[0:1] op_sel_hi:[1,0]
	v_pk_mul_f32 v[22:23], v[22:23], v[0:1] op_sel_hi:[1,0]
	v_pk_mul_f32 v[20:21], v[20:21], v[0:1] op_sel_hi:[1,0]
	v_pk_mul_f32 v[18:19], v[18:19], v[0:1] op_sel_hi:[1,0]
	v_pk_mul_f32 v[16:17], v[16:17], v[0:1] op_sel_hi:[1,0]
	v_pk_mul_f32 v[14:15], v[14:15], v[0:1] op_sel_hi:[1,0]
	v_pk_mul_f32 v[12:13], v[12:13], v[0:1] op_sel_hi:[1,0]
	v_pk_mul_f32 v[10:11], v[10:11], v[0:1] op_sel_hi:[1,0]
	v_pk_mul_f32 v[8:9], v[8:9], v[0:1] op_sel_hi:[1,0]
	v_pk_mul_f32 v[6:7], v[6:7], v[0:1] op_sel_hi:[1,0]
	v_pk_mul_f32 v[4:5], v[4:5], v[0:1] op_sel_hi:[1,0]
	v_pk_mul_f32 v[2:3], v[2:3], v[0:1] op_sel_hi:[1,0]

.LBB0_91:
	s_cmp_lt_u32 s45, s67
	s_cselect_b64 s[40:41], -1, 0
	s_cmp_ge_u32 s45, s67
	s_cselect_b64 s[34:35], -1, 0
	s_and_b64 vcc, exec, s[34:35]
	s_cbranch_vccnz .LBB0_93
	global_load_dwordx4 v[148:151], v202, s[88:89]
	global_load_dwordx4 v[152:155], v200, s[88:89]
	global_load_dwordx4 v[156:159], v196, s[88:89]
	global_load_dwordx4 v[160:163], v198, s[88:89]

.LBB0_109:
	s_cmp_lt_u32 s30, s67
	s_cselect_b64 s[26:27], -1, 0
	s_cmp_ge_u32 s30, s67
	s_cselect_b64 s[24:25], -1, 0
	s_and_b64 vcc, exec, s[24:25]
	s_cbranch_vccnz .LBB0_111
	global_load_dwordx4 v[146:149], v174, s[88:89]
	global_load_dwordx4 v[150:153], v176, s[88:89]
	global_load_dwordx4 v[154:157], v178, s[88:89]
	global_load_dwordx4 v[158:161], v172, s[88:89]
	global_load_dwordx4 v[162:165], v170, s[88:89]
